# post1 RWKV g-gate stage: 12 bf16 loads per thread issued together (prev/next rows unconditional + masked) instead of dependent round trips
# speedup vs baseline: 1.0302x; 1.0052x over previous
.LBB0_1180:
	s_lshl_b32 s45, s44, 4
	s_mov_b32 s6, 0xffffde00
	s_mov_b32 s7, -1
	s_mov_b32 s24, 0x2200
	s_mov_b32 s25, 0
	v_lshlrev_b32_e32 v98, 1, v100
	global_load_dword v88, v[102:103], off
	global_load_dword v89, v[104:105], off
	v_or_b32_e32 v132, s45, v101
	v_mov_b64_e32 v[136:137], s[38:39]
	v_mad_i64_i32 v[136:137], s[0:1], v132, s35, v[136:137]
	v_lshl_add_u64 v[136:137], v[136:137], 0, v[98:99]
	v_lshl_add_u64 v[136:137], v[136:137], 0, s[20:21]
	v_lshl_add_u64 v[144:145], v[136:137], 0, s[6:7]
	v_lshl_add_u64 v[146:147], v[136:137], 0, s[24:25]
	global_load_ushort v148, v[136:137], off
	global_load_ushort v152, v[144:145], off
	global_load_ushort v156, v[146:147], off
	v_or_b32_e32 v133, s45, v120
	v_mov_b64_e32 v[138:139], s[38:39]
	v_mad_i64_i32 v[138:139], s[0:1], v133, s35, v[138:139]
	v_lshl_add_u64 v[138:139], v[138:139], 0, v[98:99]
	v_lshl_add_u64 v[138:139], v[138:139], 0, s[20:21]
	v_lshl_add_u64 v[144:145], v[138:139], 0, s[6:7]
	v_lshl_add_u64 v[146:147], v[138:139], 0, s[24:25]
	global_load_ushort v149, v[138:139], off
	global_load_ushort v153, v[144:145], off
	global_load_ushort v157, v[146:147], off
	v_or_b32_e32 v134, s45, v122
	v_mov_b64_e32 v[140:141], s[38:39]
	v_mad_i64_i32 v[140:141], s[0:1], v134, s35, v[140:141]
	v_lshl_add_u64 v[140:141], v[140:141], 0, v[98:99]
	v_lshl_add_u64 v[140:141], v[140:141], 0, s[20:21]
	v_lshl_add_u64 v[144:145], v[140:141], 0, s[6:7]
	v_lshl_add_u64 v[146:147], v[140:141], 0, s[24:25]
	global_load_ushort v150, v[140:141], off
	global_load_ushort v154, v[144:145], off
	global_load_ushort v158, v[146:147], off
	v_or_b32_e32 v135, s45, v123
	v_mov_b64_e32 v[142:143], s[38:39]
	v_mad_i64_i32 v[142:143], s[0:1], v135, s35, v[142:143]
	v_lshl_add_u64 v[142:143], v[142:143], 0, v[98:99]
	v_lshl_add_u64 v[142:143], v[142:143], 0, s[20:21]
	v_lshl_add_u64 v[144:145], v[142:143], 0, s[6:7]
	v_lshl_add_u64 v[146:147], v[142:143], 0, s[24:25]
	global_load_ushort v151, v[142:143], off
	global_load_ushort v155, v[144:145], off
	global_load_ushort v159, v[146:147], off
	s_waitcnt vmcnt(0)
	v_and_b32_e32 v90, v127, v132
	v_lshlrev_b32_e32 v91, 16, v148
	v_lshlrev_b32_e32 v92, 16, v152
	v_lshlrev_b32_e32 v93, 16, v156
	v_cmp_ne_u32_e32 vcc, 0, v90
	s_nop 1
	v_cndmask_b32_e32 v92, 0, v92, vcc
	v_cmp_ne_u32_e32 vcc, s40, v90
	s_nop 1
	v_cndmask_b32_e32 v93, 0, v93, vcc
	v_sub_f32_e32 v92, v92, v91
	v_sub_f32_e32 v93, v93, v91
	v_mul_f32_e32 v92, v92, v88
	v_mul_f32_e32 v93, v93, v89
	v_add_f32_e32 v92, v92, v91
	v_add_f32_e32 v92, v92, v93
	v_mul_f32_e32 v92, 0xbfb8aa3b, v92
	v_exp_f32_e32 v92, v92
	s_nop 0
	v_add_f32_e32 v95, 1.0, v92
	v_div_scale_f32 v93, s[0:1], v95, v95, 1.0
	v_rcp_f32_e32 v94, v93
	v_div_scale_f32 v112, vcc, 1.0, v95, 1.0
	v_fma_f32 v113, -v93, v94, 1.0
	v_fmac_f32_e32 v94, v113, v94
	v_mul_f32_e32 v113, v112, v94
	v_fma_f32 v114, -v93, v113, v112
	v_fmac_f32_e32 v113, v114, v94
	v_fma_f32 v93, -v93, v113, v112
	v_div_fmas_f32 v112, v93, v94, v113
	v_div_fixup_f32 v92, v112, v95, 1.0
	ds_write_b32 v109, v92
	v_and_b32_e32 v90, v127, v133
	v_lshlrev_b32_e32 v91, 16, v149
	v_lshlrev_b32_e32 v92, 16, v153
	v_lshlrev_b32_e32 v93, 16, v157
	v_cmp_ne_u32_e32 vcc, 0, v90
	s_nop 1
	v_cndmask_b32_e32 v92, 0, v92, vcc
	v_cmp_ne_u32_e32 vcc, s40, v90
	s_nop 1
	v_cndmask_b32_e32 v93, 0, v93, vcc
	v_sub_f32_e32 v92, v92, v91
	v_sub_f32_e32 v93, v93, v91
	v_mul_f32_e32 v92, v92, v88
	v_mul_f32_e32 v93, v93, v89
	v_add_f32_e32 v92, v92, v91
	v_add_f32_e32 v92, v92, v93
	v_mul_f32_e32 v92, 0xbfb8aa3b, v92
	v_exp_f32_e32 v92, v92
	s_nop 0
	v_add_f32_e32 v95, 1.0, v92
	v_div_scale_f32 v93, s[0:1], v95, v95, 1.0
	v_rcp_f32_e32 v94, v93
	v_div_scale_f32 v112, vcc, 1.0, v95, 1.0
	v_fma_f32 v113, -v93, v94, 1.0
	v_fmac_f32_e32 v94, v113, v94
	v_mul_f32_e32 v113, v112, v94
	v_fma_f32 v114, -v93, v113, v112
	v_fmac_f32_e32 v113, v114, v94
	v_fma_f32 v93, -v93, v113, v112
	v_div_fmas_f32 v112, v93, v94, v113
	v_div_fixup_f32 v92, v112, v95, 1.0
	ds_write_b32 v121, v92
	v_and_b32_e32 v90, v127, v134
	v_lshlrev_b32_e32 v91, 16, v150
	v_lshlrev_b32_e32 v92, 16, v154
	v_lshlrev_b32_e32 v93, 16, v158
	v_cmp_ne_u32_e32 vcc, 0, v90
	s_nop 1
	v_cndmask_b32_e32 v92, 0, v92, vcc
	v_cmp_ne_u32_e32 vcc, s40, v90
	s_nop 1
	v_cndmask_b32_e32 v93, 0, v93, vcc
	v_sub_f32_e32 v92, v92, v91
	v_sub_f32_e32 v93, v93, v91
	v_mul_f32_e32 v92, v92, v88
	v_mul_f32_e32 v93, v93, v89
	v_add_f32_e32 v92, v92, v91
	v_add_f32_e32 v92, v92, v93
	v_mul_f32_e32 v92, 0xbfb8aa3b, v92
	v_exp_f32_e32 v92, v92
	s_nop 0
	v_add_f32_e32 v95, 1.0, v92
	v_div_scale_f32 v93, s[0:1], v95, v95, 1.0
	v_rcp_f32_e32 v94, v93
	v_div_scale_f32 v112, vcc, 1.0, v95, 1.0
	v_fma_f32 v113, -v93, v94, 1.0
	v_fmac_f32_e32 v94, v113, v94
	v_mul_f32_e32 v113, v112, v94
	v_fma_f32 v114, -v93, v113, v112
	v_fmac_f32_e32 v113, v114, v94
	v_fma_f32 v93, -v93, v113, v112
	v_div_fmas_f32 v112, v93, v94, v113
	v_div_fixup_f32 v92, v112, v95, 1.0
	ds_write_b32 v109, v92 offset:32
	v_and_b32_e32 v90, v127, v135
	v_lshlrev_b32_e32 v91, 16, v151
	v_lshlrev_b32_e32 v92, 16, v155
	v_lshlrev_b32_e32 v93, 16, v159
	v_cmp_ne_u32_e32 vcc, 0, v90
	s_nop 1
	v_cndmask_b32_e32 v92, 0, v92, vcc
	v_cmp_ne_u32_e32 vcc, s40, v90
	s_nop 1
	v_cndmask_b32_e32 v93, 0, v93, vcc
	v_sub_f32_e32 v92, v92, v91
	v_sub_f32_e32 v93, v93, v91
	v_mul_f32_e32 v92, v92, v88
	v_mul_f32_e32 v93, v93, v89
	v_add_f32_e32 v92, v92, v91
	v_add_f32_e32 v92, v92, v93
	v_mul_f32_e32 v92, 0xbfb8aa3b, v92
	v_exp_f32_e32 v92, v92
	s_nop 0
	v_add_f32_e32 v95, 1.0, v92
	v_div_scale_f32 v93, s[0:1], v95, v95, 1.0
	v_rcp_f32_e32 v94, v93
	v_div_scale_f32 v112, vcc, 1.0, v95, 1.0
	v_fma_f32 v113, -v93, v94, 1.0
	v_fmac_f32_e32 v94, v113, v94
	v_mul_f32_e32 v113, v112, v94
	v_fma_f32 v114, -v93, v113, v112
	v_fmac_f32_e32 v113, v114, v94
	v_fma_f32 v93, -v93, v113, v112
	v_div_fmas_f32 v112, v93, v94, v113
	v_div_fixup_f32 v92, v112, v95, 1.0
	ds_write_b32 v124, v92
	v_mov_b32_e32 v88, 0
	v_mov_b32_e32 v89, 0
	v_mov_b32_e32 v90, 0
	v_mov_b32_e32 v91, 0
	v_mov_b32_e32 v92, 0
	v_mov_b32_e32 v93, 0
	v_mov_b32_e32 v94, 0
	v_mov_b32_e32 v95, 0
	v_mov_b32_e32 v112, 0
	v_mov_b32_e32 v113, 0
	v_mov_b32_e32 v114, 0
	v_mov_b32_e32 v115, 0
	v_mov_b32_e32 v116, 0
	v_mov_b32_e32 v117, 0
	v_mov_b32_e32 v118, 0
	v_mov_b32_e32 v119, 0
	s_mov_b32 s6, 0
	s_mov_b64 s[0:1], 0
	s_waitcnt lgkmcnt(0)
	s_barrier
	v_readlane_b32 s0, v255, 33
	v_readlane_b32 s1, v255, 34
	v_and_b32_e32 v151, 63, v164
	v_lshrrev_b32_e32 v152, 6, v164
	v_lshlrev_b32_e32 v148, 2, v151
	v_lshrrev_b32_e32 v153, 4, v151
	v_and_b32_e32 v154, 15, v151
	v_lshlrev_b32_e32 v149, 11, v153
	v_lshl_add_u32 v149, v152, 8, v149
	v_lshl_add_u32 v149, v154, 4, v149
	v_lshlrev_b32_e32 v150, 13, v153
	v_lshl_add_u32 v150, v152, 8, v150
	v_lshl_add_u32 v150, v154, 4, v150
	v_add_u32_e32 v150, 0x2000, v150
	global_load_dwordx4 v[136:139], v149, s[0:1]
	v_add_u32_e32 v149, 0x2000, v149
	ds_read_b32 v132, v148 offset:0
	global_load_dwordx4 v[140:143], v149, s[0:1]
	v_add_u32_e32 v149, 0x2000, v149
	ds_read_b32 v133, v148 offset:256
	global_load_dwordx4 v[144:147], v149, s[0:1]
	v_add_u32_e32 v149, 0x2000, v149
	ds_read_b32 v134, v148 offset:512
	s_waitcnt vmcnt(2) lgkmcnt(2)
	v_mfma_f32_16x16x4_f32 v[88:91], v132, v136, v[88:91]
	v_mfma_f32_16x16x4_f32 v[92:95], v132, v137, v[92:95]
	v_mfma_f32_16x16x4_f32 v[112:115], v132, v138, v[112:115]
	v_mfma_f32_16x16x4_f32 v[116:119], v132, v139, v[116:119]
	global_load_dwordx4 v[136:139], v149, s[0:1]
	v_add_u32_e32 v149, 0x2000, v149
	ds_read_b32 v132, v148 offset:768
	s_waitcnt vmcnt(2) lgkmcnt(2)
	v_mfma_f32_16x16x4_f32 v[88:91], v133, v140, v[88:91]
	v_mfma_f32_16x16x4_f32 v[92:95], v133, v141, v[92:95]
	v_mfma_f32_16x16x4_f32 v[112:115], v133, v142, v[112:115]
	v_mfma_f32_16x16x4_f32 v[116:119], v133, v143, v[116:119]
	global_load_dwordx4 v[140:143], v149, s[0:1]
	v_add_u32_e32 v149, 0x2000, v149
	ds_read_b32 v133, v148 offset:1024
	s_waitcnt vmcnt(2) lgkmcnt(2)
	v_mfma_f32_16x16x4_f32 v[88:91], v134, v144, v[88:91]
	v_mfma_f32_16x16x4_f32 v[92:95], v134, v145, v[92:95]
	v_mfma_f32_16x16x4_f32 v[112:115], v134, v146, v[112:115]
	v_mfma_f32_16x16x4_f32 v[116:119], v134, v147, v[116:119]
	global_load_dwordx4 v[144:147], v149, s[0:1]
	v_add_u32_e32 v149, 0x2000, v149
	ds_read_b32 v134, v148 offset:1280
	s_waitcnt vmcnt(2) lgkmcnt(2)
	v_mfma_f32_16x16x4_f32 v[88:91], v132, v136, v[88:91]
	v_mfma_f32_16x16x4_f32 v[92:95], v132, v137, v[92:95]
	v_mfma_f32_16x16x4_f32 v[112:115], v132, v138, v[112:115]
	v_mfma_f32_16x16x4_f32 v[116:119], v132, v139, v[116:119]
	global_load_dwordx4 v[136:139], v149, s[0:1]
	v_add_u32_e32 v149, 0x2000, v149
	ds_read_b32 v132, v148 offset:1536
	s_waitcnt vmcnt(2) lgkmcnt(2)
	v_mfma_f32_16x16x4_f32 v[88:91], v133, v140, v[88:91]
	v_mfma_f32_16x16x4_f32 v[92:95], v133, v141, v[92:95]
	v_mfma_f32_16x16x4_f32 v[112:115], v133, v142, v[112:115]
	v_mfma_f32_16x16x4_f32 v[116:119], v133, v143, v[116:119]
	global_load_dwordx4 v[140:143], v149, s[0:1]
	v_add_u32_e32 v149, 0x2000, v149
	ds_read_b32 v133, v148 offset:1792
	s_waitcnt vmcnt(2) lgkmcnt(2)
	v_mfma_f32_16x16x4_f32 v[88:91], v134, v144, v[88:91]
	v_mfma_f32_16x16x4_f32 v[92:95], v134, v145, v[92:95]
	v_mfma_f32_16x16x4_f32 v[112:115], v134, v146, v[112:115]
	v_mfma_f32_16x16x4_f32 v[116:119], v134, v147, v[116:119]
	global_load_dwordx4 v[144:147], v149, s[0:1]
	v_add_u32_e32 v149, 0x2000, v149
	ds_read_b32 v134, v148 offset:2048
	s_waitcnt vmcnt(2) lgkmcnt(2)
	v_mfma_f32_16x16x4_f32 v[88:91], v132, v136, v[88:91]
	v_mfma_f32_16x16x4_f32 v[92:95], v132, v137, v[92:95]
	v_mfma_f32_16x16x4_f32 v[112:115], v132, v138, v[112:115]
	v_mfma_f32_16x16x4_f32 v[116:119], v132, v139, v[116:119]
	global_load_dwordx4 v[136:139], v149, s[0:1]
	v_add_u32_e32 v149, 0x2000, v149
	ds_read_b32 v132, v148 offset:2304
	s_waitcnt vmcnt(2) lgkmcnt(2)
	v_mfma_f32_16x16x4_f32 v[88:91], v133, v140, v[88:91]
	v_mfma_f32_16x16x4_f32 v[92:95], v133, v141, v[92:95]
	v_mfma_f32_16x16x4_f32 v[112:115], v133, v142, v[112:115]
	v_mfma_f32_16x16x4_f32 v[116:119], v133, v143, v[116:119]
	global_load_dwordx4 v[140:143], v149, s[0:1]
	v_add_u32_e32 v149, 0x2000, v149
	ds_read_b32 v133, v148 offset:2560
	s_waitcnt vmcnt(2) lgkmcnt(2)
	v_mfma_f32_16x16x4_f32 v[88:91], v134, v144, v[88:91]
	v_mfma_f32_16x16x4_f32 v[92:95], v134, v145, v[92:95]
	v_mfma_f32_16x16x4_f32 v[112:115], v134, v146, v[112:115]
	v_mfma_f32_16x16x4_f32 v[116:119], v134, v147, v[116:119]
	global_load_dwordx4 v[144:147], v149, s[0:1]
	v_add_u32_e32 v149, 0x2000, v149
	ds_read_b32 v134, v148 offset:2816
	s_waitcnt vmcnt(2) lgkmcnt(2)
	v_mfma_f32_16x16x4_f32 v[88:91], v132, v136, v[88:91]
	v_mfma_f32_16x16x4_f32 v[92:95], v132, v137, v[92:95]
	v_mfma_f32_16x16x4_f32 v[112:115], v132, v138, v[112:115]
	v_mfma_f32_16x16x4_f32 v[116:119], v132, v139, v[116:119]
	global_load_dwordx4 v[136:139], v149, s[0:1]
	v_add_u32_e32 v149, 0x2000, v149
	ds_read_b32 v132, v148 offset:3072
	s_waitcnt vmcnt(2) lgkmcnt(2)
	v_mfma_f32_16x16x4_f32 v[88:91], v133, v140, v[88:91]
	v_mfma_f32_16x16x4_f32 v[92:95], v133, v141, v[92:95]
	v_mfma_f32_16x16x4_f32 v[112:115], v133, v142, v[112:115]
	v_mfma_f32_16x16x4_f32 v[116:119], v133, v143, v[116:119]
	global_load_dwordx4 v[140:143], v149, s[0:1]
	v_add_u32_e32 v149, 0x2000, v149
	ds_read_b32 v133, v148 offset:3328
	s_waitcnt vmcnt(2) lgkmcnt(2)
	v_mfma_f32_16x16x4_f32 v[88:91], v134, v144, v[88:91]
	v_mfma_f32_16x16x4_f32 v[92:95], v134, v145, v[92:95]
	v_mfma_f32_16x16x4_f32 v[112:115], v134, v146, v[112:115]
	v_mfma_f32_16x16x4_f32 v[116:119], v134, v147, v[116:119]
	global_load_dwordx4 v[144:147], v149, s[0:1]
	v_add_u32_e32 v149, 0x2000, v149
	ds_read_b32 v134, v148 offset:3584
	s_waitcnt vmcnt(2) lgkmcnt(2)
	v_mfma_f32_16x16x4_f32 v[88:91], v132, v136, v[88:91]
	v_mfma_f32_16x16x4_f32 v[92:95], v132, v137, v[92:95]
	v_mfma_f32_16x16x4_f32 v[112:115], v132, v138, v[112:115]
	v_mfma_f32_16x16x4_f32 v[116:119], v132, v139, v[116:119]
	global_load_dwordx4 v[136:139], v149, s[0:1]
	v_add_u32_e32 v149, 0x2000, v149
	ds_read_b32 v132, v148 offset:3840
	s_waitcnt vmcnt(2) lgkmcnt(2)
	v_mfma_f32_16x16x4_f32 v[88:91], v133, v140, v[88:91]
	v_mfma_f32_16x16x4_f32 v[92:95], v133, v141, v[92:95]
	v_mfma_f32_16x16x4_f32 v[112:115], v133, v142, v[112:115]
	v_mfma_f32_16x16x4_f32 v[116:119], v133, v143, v[116:119]
	global_load_dwordx4 v[140:143], v149, s[0:1]
	v_add_u32_e32 v149, 0x2000, v149
	ds_read_b32 v133, v148 offset:4096
	s_waitcnt vmcnt(2) lgkmcnt(2)
	v_mfma_f32_16x16x4_f32 v[88:91], v134, v144, v[88:91]
	v_mfma_f32_16x16x4_f32 v[92:95], v134, v145, v[92:95]
	v_mfma_f32_16x16x4_f32 v[112:115], v134, v146, v[112:115]
	v_mfma_f32_16x16x4_f32 v[116:119], v134, v147, v[116:119]
	global_load_dwordx4 v[144:147], v149, s[0:1]
	v_add_u32_e32 v149, 0x2000, v149
	ds_read_b32 v134, v148 offset:4352
	s_waitcnt vmcnt(2) lgkmcnt(2)
	v_mfma_f32_16x16x4_f32 v[88:91], v132, v136, v[88:91]
	v_mfma_f32_16x16x4_f32 v[92:95], v132, v137, v[92:95]
	v_mfma_f32_16x16x4_f32 v[112:115], v132, v138, v[112:115]
	v_mfma_f32_16x16x4_f32 v[116:119], v132, v139, v[116:119]
	global_load_dwordx4 v[136:139], v149, s[0:1]
	v_add_u32_e32 v149, 0x2000, v149
	ds_read_b32 v132, v148 offset:4608
	s_waitcnt vmcnt(2) lgkmcnt(2)
	v_mfma_f32_16x16x4_f32 v[88:91], v133, v140, v[88:91]
	v_mfma_f32_16x16x4_f32 v[92:95], v133, v141, v[92:95]
	v_mfma_f32_16x16x4_f32 v[112:115], v133, v142, v[112:115]
	v_mfma_f32_16x16x4_f32 v[116:119], v133, v143, v[116:119]
	global_load_dwordx4 v[140:143], v149, s[0:1]
	v_add_u32_e32 v149, 0x2000, v149
	ds_read_b32 v133, v148 offset:4864
	s_waitcnt vmcnt(2) lgkmcnt(2)
	v_mfma_f32_16x16x4_f32 v[88:91], v134, v144, v[88:91]
	v_mfma_f32_16x16x4_f32 v[92:95], v134, v145, v[92:95]
	v_mfma_f32_16x16x4_f32 v[112:115], v134, v146, v[112:115]
	v_mfma_f32_16x16x4_f32 v[116:119], v134, v147, v[116:119]
	global_load_dwordx4 v[144:147], v149, s[0:1]
	v_add_u32_e32 v149, 0x2000, v149
	ds_read_b32 v134, v148 offset:5120
	s_waitcnt vmcnt(2) lgkmcnt(2)
	v_mfma_f32_16x16x4_f32 v[88:91], v132, v136, v[88:91]
	v_mfma_f32_16x16x4_f32 v[92:95], v132, v137, v[92:95]
	v_mfma_f32_16x16x4_f32 v[112:115], v132, v138, v[112:115]
	v_mfma_f32_16x16x4_f32 v[116:119], v132, v139, v[116:119]
	global_load_dwordx4 v[136:139], v149, s[0:1]
	v_add_u32_e32 v149, 0x2000, v149
	ds_read_b32 v132, v148 offset:5376
	s_waitcnt vmcnt(2) lgkmcnt(2)
	v_mfma_f32_16x16x4_f32 v[88:91], v133, v140, v[88:91]
	v_mfma_f32_16x16x4_f32 v[92:95], v133, v141, v[92:95]
	v_mfma_f32_16x16x4_f32 v[112:115], v133, v142, v[112:115]
	v_mfma_f32_16x16x4_f32 v[116:119], v133, v143, v[116:119]
	global_load_dwordx4 v[140:143], v149, s[0:1]
	v_add_u32_e32 v149, 0x2000, v149
	ds_read_b32 v133, v148 offset:5632
	s_waitcnt vmcnt(2) lgkmcnt(2)
	v_mfma_f32_16x16x4_f32 v[88:91], v134, v144, v[88:91]
	v_mfma_f32_16x16x4_f32 v[92:95], v134, v145, v[92:95]
	v_mfma_f32_16x16x4_f32 v[112:115], v134, v146, v[112:115]
	v_mfma_f32_16x16x4_f32 v[116:119], v134, v147, v[116:119]
	global_load_dwordx4 v[144:147], v149, s[0:1]
	v_add_u32_e32 v149, 0x2000, v149
	ds_read_b32 v134, v148 offset:5888
	s_waitcnt vmcnt(2) lgkmcnt(2)
	v_mfma_f32_16x16x4_f32 v[88:91], v132, v136, v[88:91]
	v_mfma_f32_16x16x4_f32 v[92:95], v132, v137, v[92:95]
	v_mfma_f32_16x16x4_f32 v[112:115], v132, v138, v[112:115]
	v_mfma_f32_16x16x4_f32 v[116:119], v132, v139, v[116:119]
	global_load_dwordx4 v[136:139], v149, s[0:1]
	v_add_u32_e32 v149, 0x2000, v149
	ds_read_b32 v132, v148 offset:6144
	s_waitcnt vmcnt(2) lgkmcnt(2)
	v_mfma_f32_16x16x4_f32 v[88:91], v133, v140, v[88:91]
	v_mfma_f32_16x16x4_f32 v[92:95], v133, v141, v[92:95]
	v_mfma_f32_16x16x4_f32 v[112:115], v133, v142, v[112:115]
	v_mfma_f32_16x16x4_f32 v[116:119], v133, v143, v[116:119]
	global_load_dwordx4 v[140:143], v149, s[0:1]
	v_add_u32_e32 v149, 0x2000, v149
	ds_read_b32 v133, v148 offset:6400
	s_waitcnt vmcnt(2) lgkmcnt(2)
	v_mfma_f32_16x16x4_f32 v[88:91], v134, v144, v[88:91]
	v_mfma_f32_16x16x4_f32 v[92:95], v134, v145, v[92:95]
	v_mfma_f32_16x16x4_f32 v[112:115], v134, v146, v[112:115]
	v_mfma_f32_16x16x4_f32 v[116:119], v134, v147, v[116:119]
	global_load_dwordx4 v[144:147], v149, s[0:1]
	v_add_u32_e32 v149, 0x2000, v149
	ds_read_b32 v134, v148 offset:6656
	s_waitcnt vmcnt(2) lgkmcnt(2)
	v_mfma_f32_16x16x4_f32 v[88:91], v132, v136, v[88:91]
	v_mfma_f32_16x16x4_f32 v[92:95], v132, v137, v[92:95]
	v_mfma_f32_16x16x4_f32 v[112:115], v132, v138, v[112:115]
	v_mfma_f32_16x16x4_f32 v[116:119], v132, v139, v[116:119]
	global_load_dwordx4 v[136:139], v149, s[0:1]
	v_add_u32_e32 v149, 0x2000, v149
	ds_read_b32 v132, v148 offset:6912
	s_waitcnt vmcnt(2) lgkmcnt(2)
	v_mfma_f32_16x16x4_f32 v[88:91], v133, v140, v[88:91]
	v_mfma_f32_16x16x4_f32 v[92:95], v133, v141, v[92:95]
	v_mfma_f32_16x16x4_f32 v[112:115], v133, v142, v[112:115]
	v_mfma_f32_16x16x4_f32 v[116:119], v133, v143, v[116:119]
	global_load_dwordx4 v[140:143], v149, s[0:1]
	v_add_u32_e32 v149, 0x2000, v149
	ds_read_b32 v133, v148 offset:7168
	s_waitcnt vmcnt(2) lgkmcnt(2)
	v_mfma_f32_16x16x4_f32 v[88:91], v134, v144, v[88:91]
	v_mfma_f32_16x16x4_f32 v[92:95], v134, v145, v[92:95]
	v_mfma_f32_16x16x4_f32 v[112:115], v134, v146, v[112:115]
	v_mfma_f32_16x16x4_f32 v[116:119], v134, v147, v[116:119]
	global_load_dwordx4 v[144:147], v149, s[0:1]
	v_add_u32_e32 v149, 0x2000, v149
	ds_read_b32 v134, v148 offset:7424
	s_waitcnt vmcnt(2) lgkmcnt(2)
	v_mfma_f32_16x16x4_f32 v[88:91], v132, v136, v[88:91]
	v_mfma_f32_16x16x4_f32 v[92:95], v132, v137, v[92:95]
	v_mfma_f32_16x16x4_f32 v[112:115], v132, v138, v[112:115]
	v_mfma_f32_16x16x4_f32 v[116:119], v132, v139, v[116:119]
	global_load_dwordx4 v[136:139], v149, s[0:1]
	v_add_u32_e32 v149, 0x2000, v149
	ds_read_b32 v132, v148 offset:7680
	s_waitcnt vmcnt(2) lgkmcnt(2)
	v_mfma_f32_16x16x4_f32 v[88:91], v133, v140, v[88:91]
	v_mfma_f32_16x16x4_f32 v[92:95], v133, v141, v[92:95]
	v_mfma_f32_16x16x4_f32 v[112:115], v133, v142, v[112:115]
	v_mfma_f32_16x16x4_f32 v[116:119], v133, v143, v[116:119]
	global_load_dwordx4 v[140:143], v149, s[0:1]
	v_add_u32_e32 v149, 0x2000, v149
	ds_read_b32 v133, v148 offset:7936
	s_waitcnt vmcnt(2) lgkmcnt(2)
	v_mfma_f32_16x16x4_f32 v[88:91], v134, v144, v[88:91]
	v_mfma_f32_16x16x4_f32 v[92:95], v134, v145, v[92:95]
	v_mfma_f32_16x16x4_f32 v[112:115], v134, v146, v[112:115]
	v_mfma_f32_16x16x4_f32 v[116:119], v134, v147, v[116:119]
	s_waitcnt vmcnt(1) lgkmcnt(1)
	v_mfma_f32_16x16x4_f32 v[88:91], v132, v136, v[88:91]
	v_mfma_f32_16x16x4_f32 v[92:95], v132, v137, v[92:95]
	v_mfma_f32_16x16x4_f32 v[112:115], v132, v138, v[112:115]
	v_mfma_f32_16x16x4_f32 v[116:119], v132, v139, v[116:119]
	s_waitcnt vmcnt(0) lgkmcnt(0)
	v_mfma_f32_16x16x4_f32 v[88:91], v133, v140, v[88:91]
	v_mfma_f32_16x16x4_f32 v[92:95], v133, v141, v[92:95]
	v_mfma_f32_16x16x4_f32 v[112:115], v133, v142, v[112:115]
	v_mfma_f32_16x16x4_f32 v[116:119], v133, v143, v[116:119]
	s_nop 15
	s_nop 3
	s_mov_b32 s46, 0
	s_mov_b64 s[24:25], -1
	ds_write_b32 v150, v88 offset:0
	ds_write_b32 v150, v89 offset:2048
	ds_write_b32 v150, v90 offset:4096
	ds_write_b32 v150, v91 offset:6144
	ds_write_b32 v150, v92 offset:4
	ds_write_b32 v150, v93 offset:2052
	ds_write_b32 v150, v94 offset:4100
	ds_write_b32 v150, v95 offset:6148
	ds_write_b32 v150, v112 offset:8
	ds_write_b32 v150, v113 offset:2056
	ds_write_b32 v150, v114 offset:4104
	ds_write_b32 v150, v115 offset:6152
	ds_write_b32 v150, v116 offset:12
	ds_write_b32 v150, v117 offset:2060
	ds_write_b32 v150, v118 offset:4108
	ds_write_b32 v150, v119 offset:6156
	s_waitcnt lgkmcnt(0)
	s_barrier
